# xcd_barrier grid poll: all 16 arrival-counter loads issued back to back (was 13 + 3 behind partial waits: two round trips per poll)
# speedup vs baseline: 1.0067x; 1.0013x over previous
; __device__ __forceinline__ unsigned xb_ld(unsigned* p)              { return __hip_atomic_load(p, __ATOMIC_RELAXED, __HIP_MEMORY_SCOPE_AGENT); }
; __device__ __forceinline__ void xcd_barrier_complete(unsigned* bar, unsigned x, unsigned& nloc, unsigned& nx) {
;     ...
;     for (;;) {
;         sum = 0u; cnt = 0u; mine = 0u;
; #pragma unroll
;         for (unsigned j = 0; j < 16; ++j) { const unsigned c = xb_ld(&bar[XB_XCNT(j)]); sum += c; cnt += (c > 0u) ? 1u : 0u; mine = (j == x) ? c : mine; }
;         if (sum == G) break;
;         __builtin_amdgcn_s_sleep(1);
;         if ((++sp & 255u) == 0u) { if (xb_ld(&bar[XB_TMO])) break; if (sp > XB_SPIN_CAP) { atomicAdd(&bar[XB_TMO], 1u); break; } }
.LBB0_49:
	v_readlane_b32 s54, v251, 54
	v_readlane_b32 s55, v251, 55
	v_readlane_b32 s58, v251, 56
	v_readlane_b32 s59, v251, 57
	v_readlane_b32 s4, v247, 8
	v_readlane_b32 s5, v247, 9
	v_readlane_b32 s4, v251, 52
	v_readlane_b32 s6, v247, 10
	v_readlane_b32 s7, v247, 11
	v_readlane_b32 s5, v251, 53
	s_nop 3
	global_load_dword v13, v3, s[6:7] offset:1024 sc1
	global_load_dword v2, v3, s[6:7] offset:1280 sc1
	global_load_dword v4, v3, s[6:7] offset:1536 sc1
	global_load_dword v5, v3, s[6:7] offset:1792 sc1
	global_load_dword v6, v3, s[6:7] offset:2048 sc1
	global_load_dword v7, v3, s[6:7] offset:2304 sc1
	global_load_dword v8, v3, s[6:7] offset:2560 sc1
	global_load_dword v9, v3, s[6:7] offset:2816 sc1
	global_load_dword v10, v3, s[6:7] offset:3072 sc1
	global_load_dword v11, v3, s[6:7] offset:3328 sc1
	global_load_dword v12, v3, s[6:7] offset:3584 sc1
	global_load_dword v14, v3, s[6:7] offset:3840 sc1
	global_load_dword v15, v3, s[4:5] sc1
	global_load_dword v16, v3, s[54:55] sc1
	global_load_dword v17, v3, s[58:59] sc1
	v_readlane_b32 s4, v251, 58
	v_readlane_b32 s5, v251, 59
	s_mov_b64 s[54:55], -1
	s_mov_b64 s[58:59], -1
	s_nop 3
	global_load_dword v18, v3, s[4:5] sc1
	s_waitcnt vmcnt(0)
	v_add_u32_e32 v19, v2, v13
	v_add_u32_e32 v19, v19, v4
	v_add_u32_e32 v19, v19, v5
	v_add_u32_e32 v19, v19, v6
	v_add_u32_e32 v19, v19, v7
	v_add_u32_e32 v19, v19, v8
	v_add_u32_e32 v19, v19, v9
	v_add_u32_e32 v19, v19, v10
	v_add_u32_e32 v19, v19, v11
	v_add_u32_e32 v19, v19, v12
	v_add_u32_e32 v19, v19, v14
	v_add_u32_e32 v19, v19, v15
	v_add_u32_e32 v19, v19, v16
	v_add_u32_e32 v19, v19, v17
	v_add_u32_e32 v19, v19, v18
	v_cmp_eq_u32_e32 vcc, s3, v19
	s_cbranch_vccnz .LBB0_48
	s_and_b32 s25, s24, 0xff
	s_cmp_eq_u32 s25, 0
	s_mov_b64 s[60:61], -1
	s_sleep 1
	s_cbranch_scc0 .LBB0_53
	v_readlane_b32 s4, v251, 50
	v_readlane_b32 s5, v251, 51
	s_nop 4
	global_load_dword v19, v3, s[4:5] sc1
	s_waitcnt vmcnt(0)
	v_cmp_eq_u32_e32 vcc, 0, v19
	s_cbranch_vccnz .LBB0_55
	s_mov_b64 s[60:61], 0

; __device__ __forceinline__ unsigned xb_ld(unsigned* p)              { return __hip_atomic_load(p, __ATOMIC_RELAXED, __HIP_MEMORY_SCOPE_AGENT); }
; __device__ __forceinline__ void xcd_barrier_complete(unsigned* bar, unsigned x, unsigned& nloc, unsigned& nx) {
;     ...
;     for (;;) {
;         sum = 0u; cnt = 0u; mine = 0u;
; #pragma unroll
;         for (unsigned j = 0; j < 16; ++j) { const unsigned c = xb_ld(&bar[XB_XCNT(j)]); sum += c; cnt += (c > 0u) ? 1u : 0u; mine = (j == x) ? c : mine; }
;         if (sum == G) break;
;         __builtin_amdgcn_s_sleep(1);
;         if ((++sp & 255u) == 0u) { if (xb_ld(&bar[XB_TMO])) break; if (sp > XB_SPIN_CAP) { atomicAdd(&bar[XB_TMO], 1u); break; } }
.LBB0_284:
	v_readlane_b32 s8, v251, 54
	v_readlane_b32 s9, v251, 55
	v_readlane_b32 s12, v251, 56
	v_readlane_b32 s13, v251, 57
	v_readlane_b32 s4, v251, 52
	v_readlane_b32 s5, v251, 53
	global_load_dword v14, v3, s[90:91] offset:1024 sc1
	global_load_dword v2, v3, s[90:91] offset:1280 sc1
	global_load_dword v4, v3, s[90:91] offset:1536 sc1
	global_load_dword v5, v3, s[90:91] offset:1792 sc1
	global_load_dword v6, v3, s[90:91] offset:2048 sc1
	global_load_dword v7, v3, s[90:91] offset:2304 sc1
	global_load_dword v8, v3, s[90:91] offset:2560 sc1
	global_load_dword v9, v3, s[90:91] offset:2816 sc1
	global_load_dword v10, v3, s[90:91] offset:3072 sc1
	global_load_dword v11, v3, s[90:91] offset:3328 sc1
	global_load_dword v12, v3, s[90:91] offset:3584 sc1
	global_load_dword v13, v3, s[90:91] offset:3840 sc1
	global_load_dword v15, v3, s[4:5] sc1
	global_load_dword v16, v3, s[8:9] sc1
	global_load_dword v17, v3, s[12:13] sc1
	v_readlane_b32 s4, v251, 58
	v_readlane_b32 s5, v251, 59
	s_mov_b64 s[8:9], -1
	s_mov_b64 s[12:13], -1
	s_nop 3
	global_load_dword v18, v3, s[4:5] sc1
	s_waitcnt vmcnt(0)
	v_add_u32_e32 v19, v2, v14
	v_add_u32_e32 v19, v19, v4
	v_add_u32_e32 v19, v19, v5
	v_add_u32_e32 v19, v19, v6
	v_add_u32_e32 v19, v19, v7
	v_add_u32_e32 v19, v19, v8
	v_add_u32_e32 v19, v19, v9
	v_add_u32_e32 v19, v19, v10
	v_add_u32_e32 v19, v19, v11
	v_add_u32_e32 v19, v19, v12
	v_add_u32_e32 v19, v19, v13
	v_add_u32_e32 v19, v19, v15
	v_add_u32_e32 v19, v19, v16
	v_add_u32_e32 v19, v19, v17
	v_add_u32_e32 v19, v19, v18
	v_cmp_eq_u32_e32 vcc, s3, v19
	s_cbranch_vccnz .LBB0_283
	s_and_b32 s8, s18, 0xff
	s_cmp_eq_u32 s8, 0
	s_mov_b64 s[8:9], -1
	s_mov_b64 s[20:21], -1
	s_sleep 1
	s_cbranch_scc0 .LBB0_288
	v_readlane_b32 s4, v251, 50
	v_readlane_b32 s5, v251, 51
	s_nop 4
	global_load_dword v19, v3, s[4:5] sc1
	s_waitcnt vmcnt(0)
	v_cmp_eq_u32_e32 vcc, 0, v19
	s_cbranch_vccnz .LBB0_290
	s_mov_b64 s[20:21], 0

; __device__ __forceinline__ unsigned xb_ld(unsigned* p)              { return __hip_atomic_load(p, __ATOMIC_RELAXED, __HIP_MEMORY_SCOPE_AGENT); }
; __device__ __forceinline__ void xcd_barrier_complete(unsigned* bar, unsigned x, unsigned& nloc, unsigned& nx) {
;     ...
;     for (;;) {
;         sum = 0u; cnt = 0u; mine = 0u;
; #pragma unroll
;         for (unsigned j = 0; j < 16; ++j) { const unsigned c = xb_ld(&bar[XB_XCNT(j)]); sum += c; cnt += (c > 0u) ? 1u : 0u; mine = (j == x) ? c : mine; }
;         if (sum == G) break;
;         __builtin_amdgcn_s_sleep(1);
;         if ((++sp & 255u) == 0u) { if (xb_ld(&bar[XB_TMO])) break; if (sp > XB_SPIN_CAP) { atomicAdd(&bar[XB_TMO], 1u); break; } }
.LBB0_375:
	v_readlane_b32 s12, v251, 54
	v_readlane_b32 s13, v251, 55
	v_readlane_b32 s20, v251, 56
	v_readlane_b32 s21, v251, 57
	v_readlane_b32 s4, v251, 52
	v_readlane_b32 s5, v251, 53
	global_load_dword v14, v3, s[90:91] offset:1024 sc1
	global_load_dword v2, v3, s[90:91] offset:1280 sc1
	global_load_dword v4, v3, s[90:91] offset:1536 sc1
	global_load_dword v5, v3, s[90:91] offset:1792 sc1
	global_load_dword v6, v3, s[90:91] offset:2048 sc1
	global_load_dword v7, v3, s[90:91] offset:2304 sc1
	global_load_dword v8, v3, s[90:91] offset:2560 sc1
	global_load_dword v9, v3, s[90:91] offset:2816 sc1
	global_load_dword v10, v3, s[90:91] offset:3072 sc1
	global_load_dword v11, v3, s[90:91] offset:3328 sc1
	global_load_dword v12, v3, s[90:91] offset:3584 sc1
	global_load_dword v13, v3, s[90:91] offset:3840 sc1
	global_load_dword v15, v3, s[4:5] sc1
	global_load_dword v16, v3, s[12:13] sc1
	global_load_dword v17, v3, s[20:21] sc1
	v_readlane_b32 s4, v251, 58
	v_readlane_b32 s5, v251, 59
	s_mov_b64 s[12:13], -1
	s_mov_b64 s[20:21], -1
	s_nop 3
	global_load_dword v18, v3, s[4:5] sc1
	s_waitcnt vmcnt(0)
	v_add_u32_e32 v19, v2, v14
	v_add_u32_e32 v19, v19, v4
	v_add_u32_e32 v19, v19, v5
	v_add_u32_e32 v19, v19, v6
	v_add_u32_e32 v19, v19, v7
	v_add_u32_e32 v19, v19, v8
	v_add_u32_e32 v19, v19, v9
	v_add_u32_e32 v19, v19, v10
	v_add_u32_e32 v19, v19, v11
	v_add_u32_e32 v19, v19, v12
	v_add_u32_e32 v19, v19, v13
	v_add_u32_e32 v19, v19, v15
	v_add_u32_e32 v19, v19, v16
	v_add_u32_e32 v19, v19, v17
	v_add_u32_e32 v19, v19, v18
	v_cmp_eq_u32_e32 vcc, s3, v19
	s_cbranch_vccnz .LBB0_374
	s_and_b32 s12, s18, 0xff
	s_cmp_eq_u32 s12, 0
	s_mov_b64 s[12:13], -1
	s_mov_b64 s[26:27], -1
	s_sleep 1
	s_cbranch_scc0 .LBB0_379
	v_readlane_b32 s4, v251, 50
	v_readlane_b32 s5, v251, 51
	s_nop 4
	global_load_dword v19, v3, s[4:5] sc1
	s_waitcnt vmcnt(0)
	v_cmp_eq_u32_e32 vcc, 0, v19
	s_cbranch_vccnz .LBB0_381
	s_mov_b64 s[26:27], 0

; __device__ __forceinline__ unsigned xb_ld(unsigned* p)              { return __hip_atomic_load(p, __ATOMIC_RELAXED, __HIP_MEMORY_SCOPE_AGENT); }
; __device__ __forceinline__ void xcd_barrier_complete(unsigned* bar, unsigned x, unsigned& nloc, unsigned& nx) {
;     ...
;     for (;;) {
;         sum = 0u; cnt = 0u; mine = 0u;
; #pragma unroll
;         for (unsigned j = 0; j < 16; ++j) { const unsigned c = xb_ld(&bar[XB_XCNT(j)]); sum += c; cnt += (c > 0u) ? 1u : 0u; mine = (j == x) ? c : mine; }
;         if (sum == G) break;
;         __builtin_amdgcn_s_sleep(1);
;         if ((++sp & 255u) == 0u) { if (xb_ld(&bar[XB_TMO])) break; if (sp > XB_SPIN_CAP) { atomicAdd(&bar[XB_TMO], 1u); break; } }
.LBB0_458:
	v_readlane_b32 s8, v251, 54
	v_readlane_b32 s9, v251, 55
	v_readlane_b32 s12, v251, 56
	v_readlane_b32 s13, v251, 57
	v_readlane_b32 s4, v251, 52
	v_readlane_b32 s5, v251, 53
	global_load_dword v14, v3, s[90:91] offset:1024 sc1
	global_load_dword v2, v3, s[90:91] offset:1280 sc1
	global_load_dword v4, v3, s[90:91] offset:1536 sc1
	global_load_dword v5, v3, s[90:91] offset:1792 sc1
	global_load_dword v6, v3, s[90:91] offset:2048 sc1
	global_load_dword v7, v3, s[90:91] offset:2304 sc1
	global_load_dword v8, v3, s[90:91] offset:2560 sc1
	global_load_dword v9, v3, s[90:91] offset:2816 sc1
	global_load_dword v10, v3, s[90:91] offset:3072 sc1
	global_load_dword v11, v3, s[90:91] offset:3328 sc1
	global_load_dword v12, v3, s[90:91] offset:3584 sc1
	global_load_dword v13, v3, s[90:91] offset:3840 sc1
	global_load_dword v15, v3, s[4:5] sc1
	global_load_dword v16, v3, s[8:9] sc1
	global_load_dword v17, v3, s[12:13] sc1
	v_readlane_b32 s4, v251, 58
	v_readlane_b32 s5, v251, 59
	s_mov_b64 s[8:9], -1
	s_mov_b64 s[12:13], -1
	s_nop 3
	global_load_dword v18, v3, s[4:5] sc1
	s_waitcnt vmcnt(0)
	v_add_u32_e32 v19, v2, v14
	v_add_u32_e32 v19, v19, v4
	v_add_u32_e32 v19, v19, v5
	v_add_u32_e32 v19, v19, v6
	v_add_u32_e32 v19, v19, v7
	v_add_u32_e32 v19, v19, v8
	v_add_u32_e32 v19, v19, v9
	v_add_u32_e32 v19, v19, v10
	v_add_u32_e32 v19, v19, v11
	v_add_u32_e32 v19, v19, v12
	v_add_u32_e32 v19, v19, v13
	v_add_u32_e32 v19, v19, v15
	v_add_u32_e32 v19, v19, v16
	v_add_u32_e32 v19, v19, v17
	v_add_u32_e32 v19, v19, v18
	v_cmp_eq_u32_e32 vcc, s18, v19
	s_cbranch_vccnz .LBB0_457
	s_and_b32 s8, s19, 0xff
	s_cmp_eq_u32 s8, 0
	s_mov_b64 s[8:9], -1
	s_mov_b64 s[20:21], -1
	s_sleep 1
	s_cbranch_scc0 .LBB0_462
	v_readlane_b32 s4, v251, 50
	v_readlane_b32 s5, v251, 51
	s_nop 4
	global_load_dword v19, v3, s[4:5] sc1
	s_waitcnt vmcnt(0)
	v_cmp_eq_u32_e32 vcc, 0, v19
	s_cbranch_vccnz .LBB0_464
	s_mov_b64 s[20:21], 0

; __device__ __forceinline__ unsigned xb_ld(unsigned* p)              { return __hip_atomic_load(p, __ATOMIC_RELAXED, __HIP_MEMORY_SCOPE_AGENT); }
; __device__ __forceinline__ void xcd_barrier_complete(unsigned* bar, unsigned x, unsigned& nloc, unsigned& nx) {
;     ...
;     for (;;) {
;         sum = 0u; cnt = 0u; mine = 0u;
; #pragma unroll
;         for (unsigned j = 0; j < 16; ++j) { const unsigned c = xb_ld(&bar[XB_XCNT(j)]); sum += c; cnt += (c > 0u) ? 1u : 0u; mine = (j == x) ? c : mine; }
;         if (sum == G) break;
;         __builtin_amdgcn_s_sleep(1);
;         if ((++sp & 255u) == 0u) { if (xb_ld(&bar[XB_TMO])) break; if (sp > XB_SPIN_CAP) { atomicAdd(&bar[XB_TMO], 1u); break; } }
.LBB0_782:
	v_readlane_b32 s8, v251, 54
	v_readlane_b32 s9, v251, 55
	v_readlane_b32 s12, v251, 56
	v_readlane_b32 s13, v251, 57
	v_readlane_b32 s4, v251, 52
	v_readlane_b32 s5, v251, 53
	global_load_dword v14, v3, s[90:91] offset:1024 sc1
	global_load_dword v2, v3, s[90:91] offset:1280 sc1
	global_load_dword v4, v3, s[90:91] offset:1536 sc1
	global_load_dword v5, v3, s[90:91] offset:1792 sc1
	global_load_dword v6, v3, s[90:91] offset:2048 sc1
	global_load_dword v7, v3, s[90:91] offset:2304 sc1
	global_load_dword v8, v3, s[90:91] offset:2560 sc1
	global_load_dword v9, v3, s[90:91] offset:2816 sc1
	global_load_dword v10, v3, s[90:91] offset:3072 sc1
	global_load_dword v11, v3, s[90:91] offset:3328 sc1
	global_load_dword v12, v3, s[90:91] offset:3584 sc1
	global_load_dword v13, v3, s[90:91] offset:3840 sc1
	global_load_dword v15, v3, s[4:5] sc1
	global_load_dword v16, v3, s[8:9] sc1
	global_load_dword v17, v3, s[12:13] sc1
	v_readlane_b32 s4, v251, 58
	v_readlane_b32 s5, v251, 59
	s_mov_b64 s[8:9], -1
	s_mov_b64 s[12:13], -1
	s_nop 3
	global_load_dword v18, v3, s[4:5] sc1
	s_waitcnt vmcnt(0)
	v_add_u32_e32 v19, v2, v14
	v_add_u32_e32 v19, v19, v4
	v_add_u32_e32 v19, v19, v5
	v_add_u32_e32 v19, v19, v6
	v_add_u32_e32 v19, v19, v7
	v_add_u32_e32 v19, v19, v8
	v_add_u32_e32 v19, v19, v9
	v_add_u32_e32 v19, v19, v10
	v_add_u32_e32 v19, v19, v11
	v_add_u32_e32 v19, v19, v12
	v_add_u32_e32 v19, v19, v13
	v_add_u32_e32 v19, v19, v15
	v_add_u32_e32 v19, v19, v16
	v_add_u32_e32 v19, v19, v17
	v_add_u32_e32 v19, v19, v18
	v_cmp_eq_u32_e32 vcc, s2, v19
	s_cbranch_vccnz .LBB0_781
	s_and_b32 s8, s3, 0xff
	s_cmp_eq_u32 s8, 0
	s_mov_b64 s[8:9], -1
	s_mov_b64 s[20:21], -1
	s_sleep 1
	s_cbranch_scc0 .LBB0_786
	v_readlane_b32 s4, v251, 50
	v_readlane_b32 s5, v251, 51
	s_nop 4
	global_load_dword v19, v3, s[4:5] sc1
	s_waitcnt vmcnt(0)
	v_cmp_eq_u32_e32 vcc, 0, v19
	s_cbranch_vccnz .LBB0_788
	s_mov_b64 s[20:21], 0
